# baseline (speedup 1.0000x reference)
; __device__ void phase0(const Params& p) {
;     ...
;     u16* __restrict__ xh = (u16*)(ws + OFF_XH);
;     float* __restrict__ rs = (float*)(ws + OFF_RS);
;     const int wave = tid >> 6, lane = tid & 63;
;     for (int row = b * 8 + wave; row < T; row += G * 8) {
;       const float* __restrict__ src = row < TPROMPT ? p.xp + (size_t)row * D : p.xs + (size_t)(row - TPROMPT) * D;
;       float4 v[8];
;       #pragma unroll
;       for (int i = 0; i < 8; ++i) v[i] = *reinterpret_cast<const float4*>(src + i * 256 + lane * 4);
;       float ss = 0.f;
;       #pragma unroll
;       for (int i = 0; i < 8; ++i) {
;         ss += v[i].x * v[i].x + v[i].y * v[i].y + v[i].z * v[i].z + v[i].w * v[i].w;
;         v2u o; o.x = pk2(v[i].x, v[i].y); o.y = pk2(v[i].z, v[i].w);
;         *reinterpret_cast<v2u*>(xh + (size_t)row * D + i * 256 + lane * 4) = o;
;       }
;       for (int off = 32; off > 0; off >>= 1) ss += __shfl_xor(ss, off);
;       if (lane == 0) rs[row] = rsqrtf(ss * (1.f / D) + EPS);
;     }
.LBB0_51:
	v_mbcnt_lo_u32_b32 v195, -1, 0
	s_lshl_b32 s10, s2, 3
	v_lshrrev_b32_e32 v100, 6, v194
	v_and_b32_e32 v101, 63, v194
	v_lshlrev_b32_e32 v102, 5, v101
	v_readfirstlane_b32 s92, v100
	v_lshlrev_b32_e32 v103, 4, v101
	v_xor_b32_e32 v104, 32, v101
	v_lshlrev_b32_e32 v104, 2, v104
	v_xor_b32_e32 v105, 16, v101
	v_lshlrev_b32_e32 v105, 2, v105
	v_xor_b32_e32 v106, 8, v101
	v_lshlrev_b32_e32 v106, 2, v106
	v_xor_b32_e32 v107, 4, v101
	v_lshlrev_b32_e32 v107, 2, v107
	v_xor_b32_e32 v108, 2, v101
	v_lshlrev_b32_e32 v108, 2, v108
	v_xor_b32_e32 v109, 1, v101
	v_lshlrev_b32_e32 v109, 2, v109
	v_mov_b32_e32 v110, 0x358637bd
	s_lshl_b32 s93, s2, 3
	s_add_i32 s92, s92, s93
	s_lshl_b32 s93, s33, 3
	s_add_u32 s96, s30, 0x35000000
	s_addc_u32 s97, s31, 0
	s_mov_b32 s101, 0x800000
	s_cmp_lt_i32 s92, 0xa000
	s_cbranch_scc0 .Lx_done
	s_cmp_lt_i32 s92, 0x8000
	s_cbranch_scc0 .Lx_sel0
	s_mov_b64 s[98:99], s[36:37]
	s_lshl_b32 s0, s92, 13
	s_branch .Lx_seld0
.Lx_sel0:
	s_mov_b64 s[98:99], s[38:39]
	s_sub_i32 s0, s92, 0x8000
	s_lshl_b32 s0, s0, 13
.Lx_seld0:
	v_add_u32_e32 v111, s0, v102
	v_add_u32_e32 v112, 0x1000, v111
	global_load_dwordx4 v[120:123], v111, s[98:99]
	global_load_dwordx4 v[124:127], v111, s[98:99] offset:16
	global_load_dwordx4 v[128:131], v111, s[98:99] offset:2048
	global_load_dwordx4 v[132:135], v111, s[98:99] offset:2064
	global_load_dwordx4 v[136:139], v112, s[98:99]
	global_load_dwordx4 v[140:143], v112, s[98:99] offset:16
	global_load_dwordx4 v[144:147], v112, s[98:99] offset:2048
	global_load_dwordx4 v[148:151], v112, s[98:99] offset:2064
.Lx_loop:
	s_add_i32 s1, s92, s93
	s_cmp_lt_i32 s1, 0xa000
	s_cbranch_scc0 .Lx_lastA
	s_cmp_lt_i32 s1, 0x8000
	s_cbranch_scc0 .Lx_sel1
	s_mov_b64 s[98:99], s[36:37]
	s_lshl_b32 s0, s1, 13
	s_branch .Lx_seld1
.Lx_sel1:
	s_mov_b64 s[98:99], s[38:39]
	s_sub_i32 s0, s1, 0x8000
	s_lshl_b32 s0, s0, 13
.Lx_seld1:
	v_add_u32_e32 v111, s0, v102
	v_add_u32_e32 v112, 0x1000, v111
	global_load_dwordx4 v[152:155], v111, s[98:99]
	global_load_dwordx4 v[156:159], v111, s[98:99] offset:16
	global_load_dwordx4 v[160:163], v111, s[98:99] offset:2048
	global_load_dwordx4 v[164:167], v111, s[98:99] offset:2064
	global_load_dwordx4 v[168:171], v112, s[98:99]
	global_load_dwordx4 v[172:175], v112, s[98:99] offset:16
	global_load_dwordx4 v[176:179], v112, s[98:99] offset:2048
	global_load_dwordx4 v[180:183], v112, s[98:99] offset:2064
	s_waitcnt vmcnt(8)
	v_pk_mul_f32 v[116:117], v[120:121], v[120:121]
	v_pk_mul_f32 v[118:119], v[122:123], v[122:123]
	v_pk_fma_f32 v[116:117], v[124:125], v[124:125], v[116:117]
	v_pk_fma_f32 v[118:119], v[126:127], v[126:127], v[118:119]
	v_pk_fma_f32 v[116:117], v[128:129], v[128:129], v[116:117]
	v_pk_fma_f32 v[118:119], v[130:131], v[130:131], v[118:119]
	v_pk_fma_f32 v[116:117], v[132:133], v[132:133], v[116:117]
	v_pk_fma_f32 v[118:119], v[134:135], v[134:135], v[118:119]
	v_pk_fma_f32 v[116:117], v[136:137], v[136:137], v[116:117]
	v_pk_fma_f32 v[118:119], v[138:139], v[138:139], v[118:119]
	v_pk_fma_f32 v[116:117], v[140:141], v[140:141], v[116:117]
	v_pk_fma_f32 v[118:119], v[142:143], v[142:143], v[118:119]
	v_pk_fma_f32 v[116:117], v[144:145], v[144:145], v[116:117]
	v_pk_fma_f32 v[118:119], v[146:147], v[146:147], v[118:119]
	v_pk_fma_f32 v[116:117], v[148:149], v[148:149], v[116:117]
	v_pk_fma_f32 v[118:119], v[150:151], v[150:151], v[118:119]
	v_pk_add_f32 v[116:117], v[116:117], v[118:119]
	v_add_f32_e32 v116, v116, v117
	s_lshl_b32 s0, s92, 12
	v_add_u32_e32 v113, s0, v103
	v_cvt_pk_bf16_f32 v120, v120, v121
	v_cvt_pk_bf16_f32 v121, v122, v123
	v_cvt_pk_bf16_f32 v122, v124, v125
	v_cvt_pk_bf16_f32 v123, v126, v127
	v_cvt_pk_bf16_f32 v128, v128, v129
	v_cvt_pk_bf16_f32 v129, v130, v131
	v_cvt_pk_bf16_f32 v130, v132, v133
	v_cvt_pk_bf16_f32 v131, v134, v135
	v_cvt_pk_bf16_f32 v136, v136, v137
	v_cvt_pk_bf16_f32 v137, v138, v139
	v_cvt_pk_bf16_f32 v138, v140, v141
	v_cvt_pk_bf16_f32 v139, v142, v143
	v_cvt_pk_bf16_f32 v144, v144, v145
	v_cvt_pk_bf16_f32 v145, v146, v147
	v_cvt_pk_bf16_f32 v146, v148, v149
	v_cvt_pk_bf16_f32 v147, v150, v151
	global_store_dwordx4 v113, v[120:123], s[96:97]
	global_store_dwordx4 v113, v[128:131], s[96:97] offset:1024
	global_store_dwordx4 v113, v[136:139], s[96:97] offset:2048
	global_store_dwordx4 v113, v[144:147], s[96:97] offset:3072
	ds_bpermute_b32 v117, v104, v116
	s_waitcnt lgkmcnt(0)
	v_add_f32_e32 v116, v116, v117
	ds_bpermute_b32 v117, v105, v116
	s_waitcnt lgkmcnt(0)
	v_add_f32_e32 v116, v116, v117
	ds_bpermute_b32 v117, v106, v116
	s_waitcnt lgkmcnt(0)
	v_add_f32_e32 v116, v116, v117
	ds_bpermute_b32 v117, v107, v116
	s_waitcnt lgkmcnt(0)
	v_add_f32_e32 v116, v116, v117
	ds_bpermute_b32 v117, v108, v116
	s_waitcnt lgkmcnt(0)
	v_add_f32_e32 v116, v116, v117
	ds_bpermute_b32 v117, v109, v116
	s_waitcnt lgkmcnt(0)
	v_add_f32_e32 v116, v116, v117
	v_fmamk_f32 v116, v116, 0x3a000000, v110
	v_mul_f32_e32 v117, 0x4b800000, v116
	v_cmp_gt_f32_e64 s[94:95], s101, v116
	s_lshl_b32 s0, s92, 2
	v_mov_b32_e32 v114, s0
	v_cndmask_b32_e64 v116, v116, v117, s[94:95]
	v_rsq_f32_e32 v116, v116
	s_nop 0
	v_mul_f32_e32 v117, 0x45800000, v116
	v_cndmask_b32_e64 v116, v116, v117, s[94:95]
	s_mov_b64 s[94:95], exec
	s_mov_b64 exec, 1
	global_store_dword v114, v116, s[30:31]
	s_mov_b64 exec, s[94:95]
	s_mov_b32 s92, s1
	s_add_i32 s1, s92, s93
	s_cmp_lt_i32 s1, 0xa000
	s_cbranch_scc0 .Lx_lastB
	s_cmp_lt_i32 s1, 0x8000
	s_cbranch_scc0 .Lx_sel2
	s_mov_b64 s[98:99], s[36:37]
	s_lshl_b32 s0, s1, 13
	s_branch .Lx_seld2

; __device__ void phase0(const Params& p) {
;     ...
;     u16* __restrict__ xh = (u16*)(ws + OFF_XH);
;     float* __restrict__ rs = (float*)(ws + OFF_RS);
;     const int wave = tid >> 6, lane = tid & 63;
;     for (int row = b * 8 + wave; row < T; row += G * 8) {
;       const float* __restrict__ src = row < TPROMPT ? p.xp + (size_t)row * D : p.xs + (size_t)(row - TPROMPT) * D;
;       float4 v[8];
;       #pragma unroll
;       for (int i = 0; i < 8; ++i) v[i] = *reinterpret_cast<const float4*>(src + i * 256 + lane * 4);
;       float ss = 0.f;
;       #pragma unroll
;       for (int i = 0; i < 8; ++i) {
;         ss += v[i].x * v[i].x + v[i].y * v[i].y + v[i].z * v[i].z + v[i].w * v[i].w;
;         v2u o; o.x = pk2(v[i].x, v[i].y); o.y = pk2(v[i].z, v[i].w);
;         *reinterpret_cast<v2u*>(xh + (size_t)row * D + i * 256 + lane * 4) = o;
;       }
;       for (int off = 32; off > 0; off >>= 1) ss += __shfl_xor(ss, off);
;       if (lane == 0) rs[row] = rsqrtf(ss * (1.f / D) + EPS);
;     }
.Lx_seld2:
	v_add_u32_e32 v111, s0, v102
	v_add_u32_e32 v112, 0x1000, v111
	global_load_dwordx4 v[120:123], v111, s[98:99]
	global_load_dwordx4 v[124:127], v111, s[98:99] offset:16
	global_load_dwordx4 v[128:131], v111, s[98:99] offset:2048
	global_load_dwordx4 v[132:135], v111, s[98:99] offset:2064
	global_load_dwordx4 v[136:139], v112, s[98:99]
	global_load_dwordx4 v[140:143], v112, s[98:99] offset:16
	global_load_dwordx4 v[144:147], v112, s[98:99] offset:2048
	global_load_dwordx4 v[148:151], v112, s[98:99] offset:2064
	s_waitcnt vmcnt(8)
	v_pk_mul_f32 v[116:117], v[152:153], v[152:153]
	v_pk_mul_f32 v[118:119], v[154:155], v[154:155]
	v_pk_fma_f32 v[116:117], v[156:157], v[156:157], v[116:117]
	v_pk_fma_f32 v[118:119], v[158:159], v[158:159], v[118:119]
	v_pk_fma_f32 v[116:117], v[160:161], v[160:161], v[116:117]
	v_pk_fma_f32 v[118:119], v[162:163], v[162:163], v[118:119]
	v_pk_fma_f32 v[116:117], v[164:165], v[164:165], v[116:117]
	v_pk_fma_f32 v[118:119], v[166:167], v[166:167], v[118:119]
	v_pk_fma_f32 v[116:117], v[168:169], v[168:169], v[116:117]
	v_pk_fma_f32 v[118:119], v[170:171], v[170:171], v[118:119]
	v_pk_fma_f32 v[116:117], v[172:173], v[172:173], v[116:117]
	v_pk_fma_f32 v[118:119], v[174:175], v[174:175], v[118:119]
	v_pk_fma_f32 v[116:117], v[176:177], v[176:177], v[116:117]
	v_pk_fma_f32 v[118:119], v[178:179], v[178:179], v[118:119]
	v_pk_fma_f32 v[116:117], v[180:181], v[180:181], v[116:117]
	v_pk_fma_f32 v[118:119], v[182:183], v[182:183], v[118:119]
	v_pk_add_f32 v[116:117], v[116:117], v[118:119]
	v_add_f32_e32 v116, v116, v117
	s_lshl_b32 s0, s92, 12
	v_add_u32_e32 v113, s0, v103
	v_cvt_pk_bf16_f32 v152, v152, v153
	v_cvt_pk_bf16_f32 v153, v154, v155
	v_cvt_pk_bf16_f32 v154, v156, v157
	v_cvt_pk_bf16_f32 v155, v158, v159
	v_cvt_pk_bf16_f32 v160, v160, v161
	v_cvt_pk_bf16_f32 v161, v162, v163
	v_cvt_pk_bf16_f32 v162, v164, v165
	v_cvt_pk_bf16_f32 v163, v166, v167
	v_cvt_pk_bf16_f32 v168, v168, v169
	v_cvt_pk_bf16_f32 v169, v170, v171
	v_cvt_pk_bf16_f32 v170, v172, v173
	v_cvt_pk_bf16_f32 v171, v174, v175
	v_cvt_pk_bf16_f32 v176, v176, v177
	v_cvt_pk_bf16_f32 v177, v178, v179
	v_cvt_pk_bf16_f32 v178, v180, v181
	v_cvt_pk_bf16_f32 v179, v182, v183
	global_store_dwordx4 v113, v[152:155], s[96:97]
	global_store_dwordx4 v113, v[160:163], s[96:97] offset:1024
	global_store_dwordx4 v113, v[168:171], s[96:97] offset:2048
	global_store_dwordx4 v113, v[176:179], s[96:97] offset:3072
	ds_bpermute_b32 v117, v104, v116
	s_waitcnt lgkmcnt(0)
	v_add_f32_e32 v116, v116, v117
	ds_bpermute_b32 v117, v105, v116
	s_waitcnt lgkmcnt(0)
	v_add_f32_e32 v116, v116, v117
	ds_bpermute_b32 v117, v106, v116
	s_waitcnt lgkmcnt(0)
	v_add_f32_e32 v116, v116, v117
	ds_bpermute_b32 v117, v107, v116
	s_waitcnt lgkmcnt(0)
	v_add_f32_e32 v116, v116, v117
	ds_bpermute_b32 v117, v108, v116
	s_waitcnt lgkmcnt(0)
	v_add_f32_e32 v116, v116, v117
	ds_bpermute_b32 v117, v109, v116
	s_waitcnt lgkmcnt(0)
	v_add_f32_e32 v116, v116, v117
	v_fmamk_f32 v116, v116, 0x3a000000, v110
	v_mul_f32_e32 v117, 0x4b800000, v116
	v_cmp_gt_f32_e64 s[94:95], s101, v116
	s_lshl_b32 s0, s92, 2
	v_mov_b32_e32 v114, s0
	v_cndmask_b32_e64 v116, v116, v117, s[94:95]
	v_rsq_f32_e32 v116, v116
	s_nop 0
	v_mul_f32_e32 v117, 0x45800000, v116
	v_cndmask_b32_e64 v116, v116, v117, s[94:95]
	s_mov_b64 s[94:95], exec
	s_mov_b64 exec, 1
	global_store_dword v114, v116, s[30:31]
	s_mov_b64 exec, s[94:95]
	s_mov_b32 s92, s1
	s_branch .Lx_loop
; __device__ void phase0(const Params& p) {
;     ...
;     u16* __restrict__ xh = (u16*)(ws + OFF_XH);
;     float* __restrict__ rs = (float*)(ws + OFF_RS);
;     const int wave = tid >> 6, lane = tid & 63;
;     for (int row = b * 8 + wave; row < T; row += G * 8) {
;       const float* __restrict__ src = row < TPROMPT ? p.xp + (size_t)row * D : p.xs + (size_t)(row - TPROMPT) * D;
;       float4 v[8];
;       #pragma unroll
;       for (int i = 0; i < 8; ++i) v[i] = *reinterpret_cast<const float4*>(src + i * 256 + lane * 4);
;       float ss = 0.f;
;       #pragma unroll
;       for (int i = 0; i < 8; ++i) {
;         ss += v[i].x * v[i].x + v[i].y * v[i].y + v[i].z * v[i].z + v[i].w * v[i].w;
;         v2u o; o.x = pk2(v[i].x, v[i].y); o.y = pk2(v[i].z, v[i].w);
;         *reinterpret_cast<v2u*>(xh + (size_t)row * D + i * 256 + lane * 4) = o;
;       }
;       for (int off = 32; off > 0; off >>= 1) ss += __shfl_xor(ss, off);
;       if (lane == 0) rs[row] = rsqrtf(ss * (1.f / D) + EPS);
;     }
.Lx_lastA:
	s_waitcnt vmcnt(0)
	v_pk_mul_f32 v[116:117], v[120:121], v[120:121]
	v_pk_mul_f32 v[118:119], v[122:123], v[122:123]
	v_pk_fma_f32 v[116:117], v[124:125], v[124:125], v[116:117]
	v_pk_fma_f32 v[118:119], v[126:127], v[126:127], v[118:119]
	v_pk_fma_f32 v[116:117], v[128:129], v[128:129], v[116:117]
	v_pk_fma_f32 v[118:119], v[130:131], v[130:131], v[118:119]
	v_pk_fma_f32 v[116:117], v[132:133], v[132:133], v[116:117]
	v_pk_fma_f32 v[118:119], v[134:135], v[134:135], v[118:119]
	v_pk_fma_f32 v[116:117], v[136:137], v[136:137], v[116:117]
	v_pk_fma_f32 v[118:119], v[138:139], v[138:139], v[118:119]
	v_pk_fma_f32 v[116:117], v[140:141], v[140:141], v[116:117]
	v_pk_fma_f32 v[118:119], v[142:143], v[142:143], v[118:119]
	v_pk_fma_f32 v[116:117], v[144:145], v[144:145], v[116:117]
	v_pk_fma_f32 v[118:119], v[146:147], v[146:147], v[118:119]
	v_pk_fma_f32 v[116:117], v[148:149], v[148:149], v[116:117]
	v_pk_fma_f32 v[118:119], v[150:151], v[150:151], v[118:119]
	v_pk_add_f32 v[116:117], v[116:117], v[118:119]
	v_add_f32_e32 v116, v116, v117
	s_lshl_b32 s0, s92, 12
	v_add_u32_e32 v113, s0, v103
	v_cvt_pk_bf16_f32 v120, v120, v121
	v_cvt_pk_bf16_f32 v121, v122, v123
	v_cvt_pk_bf16_f32 v122, v124, v125
	v_cvt_pk_bf16_f32 v123, v126, v127
	v_cvt_pk_bf16_f32 v128, v128, v129
	v_cvt_pk_bf16_f32 v129, v130, v131
	v_cvt_pk_bf16_f32 v130, v132, v133
	v_cvt_pk_bf16_f32 v131, v134, v135
	v_cvt_pk_bf16_f32 v136, v136, v137
	v_cvt_pk_bf16_f32 v137, v138, v139
	v_cvt_pk_bf16_f32 v138, v140, v141
	v_cvt_pk_bf16_f32 v139, v142, v143
	v_cvt_pk_bf16_f32 v144, v144, v145
	v_cvt_pk_bf16_f32 v145, v146, v147
	v_cvt_pk_bf16_f32 v146, v148, v149
	v_cvt_pk_bf16_f32 v147, v150, v151
	global_store_dwordx4 v113, v[120:123], s[96:97]
	global_store_dwordx4 v113, v[128:131], s[96:97] offset:1024
	global_store_dwordx4 v113, v[136:139], s[96:97] offset:2048
	global_store_dwordx4 v113, v[144:147], s[96:97] offset:3072
	ds_bpermute_b32 v117, v104, v116
	s_waitcnt lgkmcnt(0)
	v_add_f32_e32 v116, v116, v117
	ds_bpermute_b32 v117, v105, v116
	s_waitcnt lgkmcnt(0)
	v_add_f32_e32 v116, v116, v117
	ds_bpermute_b32 v117, v106, v116
	s_waitcnt lgkmcnt(0)
	v_add_f32_e32 v116, v116, v117
	ds_bpermute_b32 v117, v107, v116
	s_waitcnt lgkmcnt(0)
	v_add_f32_e32 v116, v116, v117
	ds_bpermute_b32 v117, v108, v116
	s_waitcnt lgkmcnt(0)
	v_add_f32_e32 v116, v116, v117
	ds_bpermute_b32 v117, v109, v116
	s_waitcnt lgkmcnt(0)
	v_add_f32_e32 v116, v116, v117
	v_fmamk_f32 v116, v116, 0x3a000000, v110
	v_mul_f32_e32 v117, 0x4b800000, v116
	v_cmp_gt_f32_e64 s[94:95], s101, v116
	s_lshl_b32 s0, s92, 2
	v_mov_b32_e32 v114, s0
	v_cndmask_b32_e64 v116, v116, v117, s[94:95]
	v_rsq_f32_e32 v116, v116
	s_nop 0
	v_mul_f32_e32 v117, 0x45800000, v116
	v_cndmask_b32_e64 v116, v116, v117, s[94:95]
	s_mov_b64 s[94:95], exec
	s_mov_b64 exec, 1
	global_store_dword v114, v116, s[30:31]
	s_mov_b64 exec, s[94:95]
	s_branch .Lx_done
.Lx_lastB:
	s_waitcnt vmcnt(0)
	v_pk_mul_f32 v[116:117], v[152:153], v[152:153]
	v_pk_mul_f32 v[118:119], v[154:155], v[154:155]
	v_pk_fma_f32 v[116:117], v[156:157], v[156:157], v[116:117]
	v_pk_fma_f32 v[118:119], v[158:159], v[158:159], v[118:119]
	v_pk_fma_f32 v[116:117], v[160:161], v[160:161], v[116:117]
	v_pk_fma_f32 v[118:119], v[162:163], v[162:163], v[118:119]
	v_pk_fma_f32 v[116:117], v[164:165], v[164:165], v[116:117]
	v_pk_fma_f32 v[118:119], v[166:167], v[166:167], v[118:119]
	v_pk_fma_f32 v[116:117], v[168:169], v[168:169], v[116:117]
	v_pk_fma_f32 v[118:119], v[170:171], v[170:171], v[118:119]
	v_pk_fma_f32 v[116:117], v[172:173], v[172:173], v[116:117]
	v_pk_fma_f32 v[118:119], v[174:175], v[174:175], v[118:119]
	v_pk_fma_f32 v[116:117], v[176:177], v[176:177], v[116:117]
	v_pk_fma_f32 v[118:119], v[178:179], v[178:179], v[118:119]
	v_pk_fma_f32 v[116:117], v[180:181], v[180:181], v[116:117]
	v_pk_fma_f32 v[118:119], v[182:183], v[182:183], v[118:119]
	v_pk_add_f32 v[116:117], v[116:117], v[118:119]
	v_add_f32_e32 v116, v116, v117
	s_lshl_b32 s0, s92, 12
	v_add_u32_e32 v113, s0, v103
	v_cvt_pk_bf16_f32 v152, v152, v153
	v_cvt_pk_bf16_f32 v153, v154, v155
	v_cvt_pk_bf16_f32 v154, v156, v157
	v_cvt_pk_bf16_f32 v155, v158, v159
	v_cvt_pk_bf16_f32 v160, v160, v161
	v_cvt_pk_bf16_f32 v161, v162, v163
	v_cvt_pk_bf16_f32 v162, v164, v165
	v_cvt_pk_bf16_f32 v163, v166, v167
	v_cvt_pk_bf16_f32 v168, v168, v169
	v_cvt_pk_bf16_f32 v169, v170, v171
	v_cvt_pk_bf16_f32 v170, v172, v173
	v_cvt_pk_bf16_f32 v171, v174, v175
	v_cvt_pk_bf16_f32 v176, v176, v177
	v_cvt_pk_bf16_f32 v177, v178, v179
	v_cvt_pk_bf16_f32 v178, v180, v181
	v_cvt_pk_bf16_f32 v179, v182, v183
	global_store_dwordx4 v113, v[152:155], s[96:97]
	global_store_dwordx4 v113, v[160:163], s[96:97] offset:1024
	global_store_dwordx4 v113, v[168:171], s[96:97] offset:2048
	global_store_dwordx4 v113, v[176:179], s[96:97] offset:3072
	ds_bpermute_b32 v117, v104, v116
	s_waitcnt lgkmcnt(0)
	v_add_f32_e32 v116, v116, v117
	ds_bpermute_b32 v117, v105, v116
	s_waitcnt lgkmcnt(0)
	v_add_f32_e32 v116, v116, v117
	ds_bpermute_b32 v117, v106, v116
	s_waitcnt lgkmcnt(0)
	v_add_f32_e32 v116, v116, v117
	ds_bpermute_b32 v117, v107, v116
	s_waitcnt lgkmcnt(0)
	v_add_f32_e32 v116, v116, v117
	ds_bpermute_b32 v117, v108, v116
	s_waitcnt lgkmcnt(0)
	v_add_f32_e32 v116, v116, v117
	ds_bpermute_b32 v117, v109, v116
	s_waitcnt lgkmcnt(0)
	v_add_f32_e32 v116, v116, v117
	v_fmamk_f32 v116, v116, 0x3a000000, v110
	v_mul_f32_e32 v117, 0x4b800000, v116
	v_cmp_gt_f32_e64 s[94:95], s101, v116
	s_lshl_b32 s0, s92, 2
	v_mov_b32_e32 v114, s0
	v_cndmask_b32_e64 v116, v116, v117, s[94:95]
	v_rsq_f32_e32 v116, v116
	s_nop 0
	v_mul_f32_e32 v117, 0x45800000, v116
	v_cndmask_b32_e64 v116, v116, v117, s[94:95]
	s_mov_b64 s[94:95], exec
	s_mov_b64 exec, 1
	global_store_dword v114, v116, s[30:31]
	s_mov_b64 exec, s[94:95]
.Lx_done:
	s_branch .LBB0_58
